# P6 rmsnorm reduction via DPP row adds + permlane16/32 swaps instead of 6 ds_bpermute round trips
# baseline (speedup 1.0000x reference)
; __device__ __forceinline__ unsigned cvt_pk_bf16(float lo, float hi) { unsigned r; asm("v_cvt_pk_bf16_f32 %0, %1, %2" : "=v"(r) : "v"(lo), "v"(hi)); return r; }
; __device__ __forceinline__ float wave_sum(float v) {
; #pragma unroll
;     for (int o = 1; o < 64; o <<= 1) v += __shfl_xor(v, o);
;     return v;
; }
; __device__ __forceinline__ void norm_apply(const f32x4 (&v)[4], const float* g, const float* sc, const float* sh, bf16_t* orow, int lane) {
;     float s = 0.f;
; #pragma unroll
;     for (int j = 0; j < 4; ++j) s += (v[j][0] * v[j][0] + v[j][1] * v[j][1]) + (v[j][2] * v[j][2] + v[j][3] * v[j][3]);
;     const float rstd = rsqrtf(wave_sum(s) * (1.f / 1024.f) + EPS);
; #pragma unroll
;     for (int j = 0; j < 4; ++j) { const int c4 = lane + 64 * j;
;         const f32x4 gg = *((const f32x4*)g + c4), cc = *((const f32x4*)sc + c4), hh = *((const f32x4*)sh + c4);
;         const f32x4 h = v[j] * rstd * gg * (cc + 1.f) + hh;
;         u32x2 w; w.x = cvt_pk_bf16(h[0], h[1]); w.y = cvt_pk_bf16(h[2], h[3]);
;         *((u32x2*)orow + c4) = w; }
; }
.Lp6_e0_go:
	v_lshlrev_b32_e32 v120, 16, v96
	v_and_b32_e32 v121, 0xffff0000, v96
	v_lshlrev_b32_e32 v122, 16, v97
	v_and_b32_e32 v123, 0xffff0000, v97
	v_lshlrev_b32_e32 v124, 16, v98
	v_and_b32_e32 v125, 0xffff0000, v98
	v_lshlrev_b32_e32 v126, 16, v99
	v_and_b32_e32 v127, 0xffff0000, v99
	v_lshlrev_b32_e32 v128, 16, v100
	v_and_b32_e32 v129, 0xffff0000, v100
	v_lshlrev_b32_e32 v130, 16, v101
	v_and_b32_e32 v131, 0xffff0000, v101
	v_lshlrev_b32_e32 v132, 16, v102
	v_and_b32_e32 v133, 0xffff0000, v102
	v_lshlrev_b32_e32 v134, 16, v103
	v_and_b32_e32 v135, 0xffff0000, v103
	s_add_i32 s22, s26, s88
	s_add_i32 s22, s22, s88
	s_min_i32 s22, s22, 0x7fff
	s_lshl_b32 s0, s22, 11
	s_add_u32 s0, s4, s0
	s_addc_u32 s1, s5, 0
	global_load_dwordx4 v[96:99], v0, s[0:1] nt
	global_load_dwordx4 v[100:103], v0, s[0:1] offset:1024 nt
	v_mul_f32_e32 v11, v120, v120
	v_mul_f32_e32 v12, v121, v121
	v_fmac_f32_e32 v11, v122, v122
	v_fmac_f32_e32 v12, v123, v123
	v_fmac_f32_e32 v11, v124, v124
	v_fmac_f32_e32 v12, v125, v125
	v_fmac_f32_e32 v11, v126, v126
	v_fmac_f32_e32 v12, v127, v127
	v_fmac_f32_e32 v11, v128, v128
	v_fmac_f32_e32 v12, v129, v129
	v_fmac_f32_e32 v11, v130, v130
	v_fmac_f32_e32 v12, v131, v131
	v_fmac_f32_e32 v11, v132, v132
	v_fmac_f32_e32 v12, v133, v133
	v_fmac_f32_e32 v11, v134, v134
	v_fmac_f32_e32 v12, v135, v135
	v_add_f32_e32 v11, v11, v12
	s_nop 1
	v_add_f32_dpp v12, v11, v11 quad_perm:[1,0,3,2] row_mask:0xf bank_mask:0xf
	s_nop 1
	v_add_f32_dpp v11, v12, v12 quad_perm:[2,3,0,1] row_mask:0xf bank_mask:0xf
	s_nop 1
	v_add_f32_dpp v12, v11, v11 row_half_mirror row_mask:0xf bank_mask:0xf
	s_nop 1
	v_add_f32_dpp v11, v12, v12 row_mirror row_mask:0xf bank_mask:0xf
	v_mov_b32_e32 v12, v11
	s_nop 1
	v_permlane16_swap_b32_e32 v12, v11
	s_nop 1
	v_add_f32_e32 v11, v11, v12
	v_mov_b32_e32 v12, v11
	s_nop 1
	v_permlane32_swap_b32_e32 v12, v11
	s_nop 1
	v_add_f32_e32 v11, v11, v12
	v_mov_b32_e32 v12, 0x358637bd
	v_fmac_f32_e32 v12, 0x3a800000, v11
	v_rsq_f32_e32 v13, v12
	s_nop 0
	s_lshl_b32 s12, s26, 11
	s_add_u32 s12, s30, s12
	s_addc_u32 s13, s31, 0
	s_add_u32 s12, s12, 0x1d00000
	s_addc_u32 s13, s13, 0
	v_mul_f32_e32 v120, v13, v120
	v_mul_f32_e32 v121, v13, v121
	v_mul_f32_e32 v122, v13, v122
	v_mul_f32_e32 v123, v13, v123
	v_mul_f32_e32 v124, v13, v124
	v_mul_f32_e32 v125, v13, v125
	v_mul_f32_e32 v126, v13, v126
	v_mul_f32_e32 v127, v13, v127
	v_mul_f32_e32 v128, v13, v128
	v_mul_f32_e32 v129, v13, v129
	v_mul_f32_e32 v130, v13, v130
	v_mul_f32_e32 v131, v13, v131
	v_mul_f32_e32 v132, v13, v132
	v_mul_f32_e32 v133, v13, v133
	v_mul_f32_e32 v134, v13, v134
	v_mul_f32_e32 v135, v13, v135
	v_mul_f32_e32 v120, v16, v120
	v_mul_f32_e32 v121, v17, v121
	v_mul_f32_e32 v122, v18, v122
	v_mul_f32_e32 v123, v19, v123
	v_mul_f32_e32 v124, v20, v124
	v_mul_f32_e32 v125, v21, v125
	v_mul_f32_e32 v126, v22, v126
	v_mul_f32_e32 v127, v23, v127
	v_mul_f32_e32 v128, v24, v128
	v_mul_f32_e32 v129, v25, v129
	v_mul_f32_e32 v130, v26, v130
	v_mul_f32_e32 v131, v27, v131
	v_mul_f32_e32 v132, v28, v132
	v_mul_f32_e32 v133, v29, v133
	v_mul_f32_e32 v134, v30, v134
	v_mul_f32_e32 v135, v31, v135
	v_add_f32_e32 v32, 1.0, v32
	v_add_f32_e32 v33, 1.0, v33
	v_add_f32_e32 v34, 1.0, v34
	v_add_f32_e32 v35, 1.0, v35
	v_add_f32_e32 v36, 1.0, v36
	v_add_f32_e32 v37, 1.0, v37
	v_add_f32_e32 v38, 1.0, v38
	v_add_f32_e32 v39, 1.0, v39
	v_add_f32_e32 v40, 1.0, v40
	v_add_f32_e32 v41, 1.0, v41
	v_add_f32_e32 v42, 1.0, v42
	v_add_f32_e32 v43, 1.0, v43
	v_add_f32_e32 v44, 1.0, v44
	v_add_f32_e32 v45, 1.0, v45
	v_add_f32_e32 v46, 1.0, v46
	v_add_f32_e32 v47, 1.0, v47
	v_fma_f32 v120, v32, v120, v48
	v_fma_f32 v121, v33, v121, v49
	v_fma_f32 v122, v34, v122, v50
	v_fma_f32 v123, v35, v123, v51
	v_fma_f32 v124, v36, v124, v52
	v_fma_f32 v125, v37, v125, v53
	v_fma_f32 v126, v38, v126, v54
	v_fma_f32 v127, v39, v127, v55
	v_fma_f32 v128, v40, v128, v56
	v_fma_f32 v129, v41, v129, v57
	v_fma_f32 v130, v42, v130, v58
	v_fma_f32 v131, v43, v131, v59
	v_fma_f32 v132, v44, v132, v60
	v_fma_f32 v133, v45, v133, v61
	v_fma_f32 v134, v46, v134, v62
	v_fma_f32 v135, v47, v135, v63
	v_cvt_pk_bf16_f32 v120, v120, v121
	v_cvt_pk_bf16_f32 v121, v122, v123
	v_cvt_pk_bf16_f32 v122, v124, v125
	v_cvt_pk_bf16_f32 v123, v126, v127
	v_cvt_pk_bf16_f32 v124, v128, v129
	v_cvt_pk_bf16_f32 v125, v130, v131
	v_cvt_pk_bf16_f32 v126, v132, v133
	v_cvt_pk_bf16_f32 v127, v134, v135
	global_store_dwordx4 v0, v[120:123], s[12:13] sc0 sc1
	global_store_dwordx4 v0, v[124:127], s[12:13] offset:1024 sc0 sc1
	s_add_i32 s26, s26, s88
	s_cmpk_gt_i32 s26, 0x7fff
	s_cbranch_scc1 .Lp6_done

; __device__ __forceinline__ unsigned cvt_pk_bf16(float lo, float hi) { unsigned r; asm("v_cvt_pk_bf16_f32 %0, %1, %2" : "=v"(r) : "v"(lo), "v"(hi)); return r; }
; __device__ __forceinline__ float wave_sum(float v) {
; #pragma unroll
;     for (int o = 1; o < 64; o <<= 1) v += __shfl_xor(v, o);
;     return v;
; }
; __device__ __forceinline__ void norm_apply(const f32x4 (&v)[4], const float* g, const float* sc, const float* sh, bf16_t* orow, int lane) {
;     float s = 0.f;
; #pragma unroll
;     for (int j = 0; j < 4; ++j) s += (v[j][0] * v[j][0] + v[j][1] * v[j][1]) + (v[j][2] * v[j][2] + v[j][3] * v[j][3]);
;     const float rstd = rsqrtf(wave_sum(s) * (1.f / 1024.f) + EPS);
; #pragma unroll
;     for (int j = 0; j < 4; ++j) { const int c4 = lane + 64 * j;
;         const f32x4 gg = *((const f32x4*)g + c4), cc = *((const f32x4*)sc + c4), hh = *((const f32x4*)sh + c4);
;         const f32x4 h = v[j] * rstd * gg * (cc + 1.f) + hh;
;         u32x2 w; w.x = cvt_pk_bf16(h[0], h[1]); w.y = cvt_pk_bf16(h[2], h[3]);
;         *((u32x2*)orow + c4) = w; }
; }
.Lp6_o0_go:
	v_lshlrev_b32_e32 v120, 16, v104
	v_and_b32_e32 v121, 0xffff0000, v104
	v_lshlrev_b32_e32 v122, 16, v105
	v_and_b32_e32 v123, 0xffff0000, v105
	v_lshlrev_b32_e32 v124, 16, v106
	v_and_b32_e32 v125, 0xffff0000, v106
	v_lshlrev_b32_e32 v126, 16, v107
	v_and_b32_e32 v127, 0xffff0000, v107
	v_lshlrev_b32_e32 v128, 16, v108
	v_and_b32_e32 v129, 0xffff0000, v108
	v_lshlrev_b32_e32 v130, 16, v109
	v_and_b32_e32 v131, 0xffff0000, v109
	v_lshlrev_b32_e32 v132, 16, v110
	v_and_b32_e32 v133, 0xffff0000, v110
	v_lshlrev_b32_e32 v134, 16, v111
	v_and_b32_e32 v135, 0xffff0000, v111
	s_add_i32 s22, s26, s88
	s_add_i32 s22, s22, s88
	s_min_i32 s22, s22, 0x7fff
	s_lshl_b32 s0, s22, 11
	s_add_u32 s0, s4, s0
	s_addc_u32 s1, s5, 0
	global_load_dwordx4 v[104:107], v0, s[0:1] nt
	global_load_dwordx4 v[108:111], v0, s[0:1] offset:1024 nt
	v_mul_f32_e32 v11, v120, v120
	v_mul_f32_e32 v12, v121, v121
	v_fmac_f32_e32 v11, v122, v122
	v_fmac_f32_e32 v12, v123, v123
	v_fmac_f32_e32 v11, v124, v124
	v_fmac_f32_e32 v12, v125, v125
	v_fmac_f32_e32 v11, v126, v126
	v_fmac_f32_e32 v12, v127, v127
	v_fmac_f32_e32 v11, v128, v128
	v_fmac_f32_e32 v12, v129, v129
	v_fmac_f32_e32 v11, v130, v130
	v_fmac_f32_e32 v12, v131, v131
	v_fmac_f32_e32 v11, v132, v132
	v_fmac_f32_e32 v12, v133, v133
	v_fmac_f32_e32 v11, v134, v134
	v_fmac_f32_e32 v12, v135, v135
	v_add_f32_e32 v11, v11, v12
	s_nop 1
	v_add_f32_dpp v12, v11, v11 quad_perm:[1,0,3,2] row_mask:0xf bank_mask:0xf
	s_nop 1
	v_add_f32_dpp v11, v12, v12 quad_perm:[2,3,0,1] row_mask:0xf bank_mask:0xf
	s_nop 1
	v_add_f32_dpp v12, v11, v11 row_half_mirror row_mask:0xf bank_mask:0xf
	s_nop 1
	v_add_f32_dpp v11, v12, v12 row_mirror row_mask:0xf bank_mask:0xf
	v_mov_b32_e32 v12, v11
	s_nop 1
	v_permlane16_swap_b32_e32 v12, v11
	s_nop 1
	v_add_f32_e32 v11, v11, v12
	v_mov_b32_e32 v12, v11
	s_nop 1
	v_permlane32_swap_b32_e32 v12, v11
	s_nop 1
	v_add_f32_e32 v11, v11, v12
	v_mov_b32_e32 v12, 0x358637bd
	v_fmac_f32_e32 v12, 0x3a800000, v11
	v_rsq_f32_e32 v13, v12
	s_nop 0
	s_lshl_b32 s12, s26, 11
	s_add_u32 s12, s30, s12
	s_addc_u32 s13, s31, 0
	s_add_u32 s12, s12, 0x1d00000
	s_addc_u32 s13, s13, 0
	v_mul_f32_e32 v120, v13, v120
	v_mul_f32_e32 v121, v13, v121
	v_mul_f32_e32 v122, v13, v122
	v_mul_f32_e32 v123, v13, v123
	v_mul_f32_e32 v124, v13, v124
	v_mul_f32_e32 v125, v13, v125
	v_mul_f32_e32 v126, v13, v126
	v_mul_f32_e32 v127, v13, v127
	v_mul_f32_e32 v128, v13, v128
	v_mul_f32_e32 v129, v13, v129
	v_mul_f32_e32 v130, v13, v130
	v_mul_f32_e32 v131, v13, v131
	v_mul_f32_e32 v132, v13, v132
	v_mul_f32_e32 v133, v13, v133
	v_mul_f32_e32 v134, v13, v134
	v_mul_f32_e32 v135, v13, v135
	v_mul_f32_e32 v120, v16, v120
	v_mul_f32_e32 v121, v17, v121
	v_mul_f32_e32 v122, v18, v122
	v_mul_f32_e32 v123, v19, v123
	v_mul_f32_e32 v124, v20, v124
	v_mul_f32_e32 v125, v21, v125
	v_mul_f32_e32 v126, v22, v126
	v_mul_f32_e32 v127, v23, v127
	v_mul_f32_e32 v128, v24, v128
	v_mul_f32_e32 v129, v25, v129
	v_mul_f32_e32 v130, v26, v130
	v_mul_f32_e32 v131, v27, v131
	v_mul_f32_e32 v132, v28, v132
	v_mul_f32_e32 v133, v29, v133
	v_mul_f32_e32 v134, v30, v134
	v_mul_f32_e32 v135, v31, v135
	v_fma_f32 v120, v32, v120, v48
	v_fma_f32 v121, v33, v121, v49
	v_fma_f32 v122, v34, v122, v50
	v_fma_f32 v123, v35, v123, v51
	v_fma_f32 v124, v36, v124, v52
	v_fma_f32 v125, v37, v125, v53
	v_fma_f32 v126, v38, v126, v54
	v_fma_f32 v127, v39, v127, v55
	v_fma_f32 v128, v40, v128, v56
	v_fma_f32 v129, v41, v129, v57
	v_fma_f32 v130, v42, v130, v58
	v_fma_f32 v131, v43, v131, v59
	v_fma_f32 v132, v44, v132, v60
	v_fma_f32 v133, v45, v133, v61
	v_fma_f32 v134, v46, v134, v62
	v_fma_f32 v135, v47, v135, v63
	v_cvt_pk_bf16_f32 v120, v120, v121
	v_cvt_pk_bf16_f32 v121, v122, v123
	v_cvt_pk_bf16_f32 v122, v124, v125
	v_cvt_pk_bf16_f32 v123, v126, v127
	v_cvt_pk_bf16_f32 v124, v128, v129
	v_cvt_pk_bf16_f32 v125, v130, v131
	v_cvt_pk_bf16_f32 v126, v132, v133
	v_cvt_pk_bf16_f32 v127, v134, v135
	global_store_dwordx4 v0, v[120:123], s[12:13] sc0 sc1
	global_store_dwordx4 v0, v[124:127], s[12:13] offset:1024 sc0 sc1
	s_add_i32 s26, s26, s88
	s_cmpk_gt_i32 s26, 0x7fff
	s_cbranch_scc1 .Lp6_done

; __device__ __forceinline__ unsigned cvt_pk_bf16(float lo, float hi) { unsigned r; asm("v_cvt_pk_bf16_f32 %0, %1, %2" : "=v"(r) : "v"(lo), "v"(hi)); return r; }
; __device__ __forceinline__ float wave_sum(float v) {
; #pragma unroll
;     for (int o = 1; o < 64; o <<= 1) v += __shfl_xor(v, o);
;     return v;
; }
; __device__ __forceinline__ void norm_apply(const f32x4 (&v)[4], const float* g, const float* sc, const float* sh, bf16_t* orow, int lane) {
;     float s = 0.f;
; #pragma unroll
;     for (int j = 0; j < 4; ++j) s += (v[j][0] * v[j][0] + v[j][1] * v[j][1]) + (v[j][2] * v[j][2] + v[j][3] * v[j][3]);
;     const float rstd = rsqrtf(wave_sum(s) * (1.f / 1024.f) + EPS);
; #pragma unroll
;     for (int j = 0; j < 4; ++j) { const int c4 = lane + 64 * j;
;         const f32x4 gg = *((const f32x4*)g + c4), cc = *((const f32x4*)sc + c4), hh = *((const f32x4*)sh + c4);
;         const f32x4 h = v[j] * rstd * gg * (cc + 1.f) + hh;
;         u32x2 w; w.x = cvt_pk_bf16(h[0], h[1]); w.y = cvt_pk_bf16(h[2], h[3]);
;         *((u32x2*)orow + c4) = w; }
; }
.Lp6_e1_go:
	v_lshlrev_b32_e32 v120, 16, v96
	v_and_b32_e32 v121, 0xffff0000, v96
	v_lshlrev_b32_e32 v122, 16, v97
	v_and_b32_e32 v123, 0xffff0000, v97
	v_lshlrev_b32_e32 v124, 16, v98
	v_and_b32_e32 v125, 0xffff0000, v98
	v_lshlrev_b32_e32 v126, 16, v99
	v_and_b32_e32 v127, 0xffff0000, v99
	v_lshlrev_b32_e32 v128, 16, v100
	v_and_b32_e32 v129, 0xffff0000, v100
	v_lshlrev_b32_e32 v130, 16, v101
	v_and_b32_e32 v131, 0xffff0000, v101
	v_lshlrev_b32_e32 v132, 16, v102
	v_and_b32_e32 v133, 0xffff0000, v102
	v_lshlrev_b32_e32 v134, 16, v103
	v_and_b32_e32 v135, 0xffff0000, v103
	s_add_i32 s22, s26, s88
	s_add_i32 s22, s22, s88
	s_min_i32 s22, s22, 0x7fff
	s_lshl_b32 s0, s22, 11
	s_add_u32 s0, s4, s0
	s_addc_u32 s1, s5, 0
	global_load_dwordx4 v[96:99], v0, s[0:1] nt
	global_load_dwordx4 v[100:103], v0, s[0:1] offset:1024 nt
	v_mul_f32_e32 v11, v120, v120
	v_mul_f32_e32 v12, v121, v121
	v_fmac_f32_e32 v11, v122, v122
	v_fmac_f32_e32 v12, v123, v123
	v_fmac_f32_e32 v11, v124, v124
	v_fmac_f32_e32 v12, v125, v125
	v_fmac_f32_e32 v11, v126, v126
	v_fmac_f32_e32 v12, v127, v127
	v_fmac_f32_e32 v11, v128, v128
	v_fmac_f32_e32 v12, v129, v129
	v_fmac_f32_e32 v11, v130, v130
	v_fmac_f32_e32 v12, v131, v131
	v_fmac_f32_e32 v11, v132, v132
	v_fmac_f32_e32 v12, v133, v133
	v_fmac_f32_e32 v11, v134, v134
	v_fmac_f32_e32 v12, v135, v135
	v_add_f32_e32 v11, v11, v12
	s_nop 1
	v_add_f32_dpp v12, v11, v11 quad_perm:[1,0,3,2] row_mask:0xf bank_mask:0xf
	s_nop 1
	v_add_f32_dpp v11, v12, v12 quad_perm:[2,3,0,1] row_mask:0xf bank_mask:0xf
	s_nop 1
	v_add_f32_dpp v12, v11, v11 row_half_mirror row_mask:0xf bank_mask:0xf
	s_nop 1
	v_add_f32_dpp v11, v12, v12 row_mirror row_mask:0xf bank_mask:0xf
	v_mov_b32_e32 v12, v11
	s_nop 1
	v_permlane16_swap_b32_e32 v12, v11
	s_nop 1
	v_add_f32_e32 v11, v11, v12
	v_mov_b32_e32 v12, v11
	s_nop 1
	v_permlane32_swap_b32_e32 v12, v11
	s_nop 1
	v_add_f32_e32 v11, v11, v12
	v_mov_b32_e32 v12, 0x358637bd
	v_fmac_f32_e32 v12, 0x3a800000, v11
	v_rsq_f32_e32 v13, v12
	s_nop 0
	s_lshl_b32 s12, s26, 11
	s_add_u32 s12, s30, s12
	s_addc_u32 s13, s31, 0
	s_add_u32 s12, s12, 0x1d00000
	s_addc_u32 s13, s13, 0
	v_mul_f32_e32 v120, v13, v120
	v_mul_f32_e32 v121, v13, v121
	v_mul_f32_e32 v122, v13, v122
	v_mul_f32_e32 v123, v13, v123
	v_mul_f32_e32 v124, v13, v124
	v_mul_f32_e32 v125, v13, v125
	v_mul_f32_e32 v126, v13, v126
	v_mul_f32_e32 v127, v13, v127
	v_mul_f32_e32 v128, v13, v128
	v_mul_f32_e32 v129, v13, v129
	v_mul_f32_e32 v130, v13, v130
	v_mul_f32_e32 v131, v13, v131
	v_mul_f32_e32 v132, v13, v132
	v_mul_f32_e32 v133, v13, v133
	v_mul_f32_e32 v134, v13, v134
	v_mul_f32_e32 v135, v13, v135
	v_mul_f32_e32 v120, v16, v120
	v_mul_f32_e32 v121, v17, v121
	v_mul_f32_e32 v122, v18, v122
	v_mul_f32_e32 v123, v19, v123
	v_mul_f32_e32 v124, v20, v124
	v_mul_f32_e32 v125, v21, v125
	v_mul_f32_e32 v126, v22, v126
	v_mul_f32_e32 v127, v23, v127
	v_mul_f32_e32 v128, v24, v128
	v_mul_f32_e32 v129, v25, v129
	v_mul_f32_e32 v130, v26, v130
	v_mul_f32_e32 v131, v27, v131
	v_mul_f32_e32 v132, v28, v132
	v_mul_f32_e32 v133, v29, v133
	v_mul_f32_e32 v134, v30, v134
	v_mul_f32_e32 v135, v31, v135
	v_add_f32_e32 v64, 1.0, v64
	v_add_f32_e32 v65, 1.0, v65
	v_add_f32_e32 v66, 1.0, v66
	v_add_f32_e32 v67, 1.0, v67
	v_add_f32_e32 v68, 1.0, v68
	v_add_f32_e32 v69, 1.0, v69
	v_add_f32_e32 v70, 1.0, v70
	v_add_f32_e32 v71, 1.0, v71
	v_add_f32_e32 v72, 1.0, v72
	v_add_f32_e32 v73, 1.0, v73
	v_add_f32_e32 v74, 1.0, v74
	v_add_f32_e32 v75, 1.0, v75
	v_add_f32_e32 v76, 1.0, v76
	v_add_f32_e32 v77, 1.0, v77
	v_add_f32_e32 v78, 1.0, v78
	v_add_f32_e32 v79, 1.0, v79
	v_fma_f32 v120, v64, v120, v80
	v_fma_f32 v121, v65, v121, v81
	v_fma_f32 v122, v66, v122, v82
	v_fma_f32 v123, v67, v123, v83
	v_fma_f32 v124, v68, v124, v84
	v_fma_f32 v125, v69, v125, v85
	v_fma_f32 v126, v70, v126, v86
	v_fma_f32 v127, v71, v127, v87
	v_fma_f32 v128, v72, v128, v88
	v_fma_f32 v129, v73, v129, v89
	v_fma_f32 v130, v74, v130, v90
	v_fma_f32 v131, v75, v131, v91
	v_fma_f32 v132, v76, v132, v92
	v_fma_f32 v133, v77, v133, v93
	v_fma_f32 v134, v78, v134, v94
	v_fma_f32 v135, v79, v135, v95
	v_cvt_pk_bf16_f32 v120, v120, v121
	v_cvt_pk_bf16_f32 v121, v122, v123
	v_cvt_pk_bf16_f32 v122, v124, v125
	v_cvt_pk_bf16_f32 v123, v126, v127
	v_cvt_pk_bf16_f32 v124, v128, v129
	v_cvt_pk_bf16_f32 v125, v130, v131
	v_cvt_pk_bf16_f32 v126, v132, v133
	v_cvt_pk_bf16_f32 v127, v134, v135
	global_store_dwordx4 v0, v[120:123], s[12:13] sc0 sc1
	global_store_dwordx4 v0, v[124:127], s[12:13] offset:1024 sc0 sc1
	s_add_i32 s26, s26, s88
	s_cmpk_gt_i32 s26, 0x7fff
	s_cbranch_scc1 .Lp6_done

; __device__ __forceinline__ unsigned cvt_pk_bf16(float lo, float hi) { unsigned r; asm("v_cvt_pk_bf16_f32 %0, %1, %2" : "=v"(r) : "v"(lo), "v"(hi)); return r; }
; __device__ __forceinline__ float wave_sum(float v) {
; #pragma unroll
;     for (int o = 1; o < 64; o <<= 1) v += __shfl_xor(v, o);
;     return v;
; }
; __device__ __forceinline__ void norm_apply(const f32x4 (&v)[4], const float* g, const float* sc, const float* sh, bf16_t* orow, int lane) {
;     float s = 0.f;
; #pragma unroll
;     for (int j = 0; j < 4; ++j) s += (v[j][0] * v[j][0] + v[j][1] * v[j][1]) + (v[j][2] * v[j][2] + v[j][3] * v[j][3]);
;     const float rstd = rsqrtf(wave_sum(s) * (1.f / 1024.f) + EPS);
; #pragma unroll
;     for (int j = 0; j < 4; ++j) { const int c4 = lane + 64 * j;
;         const f32x4 gg = *((const f32x4*)g + c4), cc = *((const f32x4*)sc + c4), hh = *((const f32x4*)sh + c4);
;         const f32x4 h = v[j] * rstd * gg * (cc + 1.f) + hh;
;         u32x2 w; w.x = cvt_pk_bf16(h[0], h[1]); w.y = cvt_pk_bf16(h[2], h[3]);
;         *((u32x2*)orow + c4) = w; }
; }
.Lp6_o1_go:
	v_lshlrev_b32_e32 v120, 16, v104
	v_and_b32_e32 v121, 0xffff0000, v104
	v_lshlrev_b32_e32 v122, 16, v105
	v_and_b32_e32 v123, 0xffff0000, v105
	v_lshlrev_b32_e32 v124, 16, v106
	v_and_b32_e32 v125, 0xffff0000, v106
	v_lshlrev_b32_e32 v126, 16, v107
	v_and_b32_e32 v127, 0xffff0000, v107
	v_lshlrev_b32_e32 v128, 16, v108
	v_and_b32_e32 v129, 0xffff0000, v108
	v_lshlrev_b32_e32 v130, 16, v109
	v_and_b32_e32 v131, 0xffff0000, v109
	v_lshlrev_b32_e32 v132, 16, v110
	v_and_b32_e32 v133, 0xffff0000, v110
	v_lshlrev_b32_e32 v134, 16, v111
	v_and_b32_e32 v135, 0xffff0000, v111
	s_add_i32 s22, s26, s88
	s_add_i32 s22, s22, s88
	s_min_i32 s22, s22, 0x7fff
	s_lshl_b32 s0, s22, 11
	s_add_u32 s0, s4, s0
	s_addc_u32 s1, s5, 0
	global_load_dwordx4 v[104:107], v0, s[0:1] nt
	global_load_dwordx4 v[108:111], v0, s[0:1] offset:1024 nt
	v_mul_f32_e32 v11, v120, v120
	v_mul_f32_e32 v12, v121, v121
	v_fmac_f32_e32 v11, v122, v122
	v_fmac_f32_e32 v12, v123, v123
	v_fmac_f32_e32 v11, v124, v124
	v_fmac_f32_e32 v12, v125, v125
	v_fmac_f32_e32 v11, v126, v126
	v_fmac_f32_e32 v12, v127, v127
	v_fmac_f32_e32 v11, v128, v128
	v_fmac_f32_e32 v12, v129, v129
	v_fmac_f32_e32 v11, v130, v130
	v_fmac_f32_e32 v12, v131, v131
	v_fmac_f32_e32 v11, v132, v132
	v_fmac_f32_e32 v12, v133, v133
	v_fmac_f32_e32 v11, v134, v134
	v_fmac_f32_e32 v12, v135, v135
	v_add_f32_e32 v11, v11, v12
	s_nop 1
	v_add_f32_dpp v12, v11, v11 quad_perm:[1,0,3,2] row_mask:0xf bank_mask:0xf
	s_nop 1
	v_add_f32_dpp v11, v12, v12 quad_perm:[2,3,0,1] row_mask:0xf bank_mask:0xf
	s_nop 1
	v_add_f32_dpp v12, v11, v11 row_half_mirror row_mask:0xf bank_mask:0xf
	s_nop 1
	v_add_f32_dpp v11, v12, v12 row_mirror row_mask:0xf bank_mask:0xf
	v_mov_b32_e32 v12, v11
	s_nop 1
	v_permlane16_swap_b32_e32 v12, v11
	s_nop 1
	v_add_f32_e32 v11, v11, v12
	v_mov_b32_e32 v12, v11
	s_nop 1
	v_permlane32_swap_b32_e32 v12, v11
	s_nop 1
	v_add_f32_e32 v11, v11, v12
	v_mov_b32_e32 v12, 0x358637bd
	v_fmac_f32_e32 v12, 0x3a800000, v11
	v_rsq_f32_e32 v13, v12
	s_nop 0
	s_lshl_b32 s12, s26, 11
	s_add_u32 s12, s30, s12
	s_addc_u32 s13, s31, 0
	s_add_u32 s12, s12, 0x1d00000
	s_addc_u32 s13, s13, 0
	v_mul_f32_e32 v120, v13, v120
	v_mul_f32_e32 v121, v13, v121
	v_mul_f32_e32 v122, v13, v122
	v_mul_f32_e32 v123, v13, v123
	v_mul_f32_e32 v124, v13, v124
	v_mul_f32_e32 v125, v13, v125
	v_mul_f32_e32 v126, v13, v126
	v_mul_f32_e32 v127, v13, v127
	v_mul_f32_e32 v128, v13, v128
	v_mul_f32_e32 v129, v13, v129
	v_mul_f32_e32 v130, v13, v130
	v_mul_f32_e32 v131, v13, v131
	v_mul_f32_e32 v132, v13, v132
	v_mul_f32_e32 v133, v13, v133
	v_mul_f32_e32 v134, v13, v134
	v_mul_f32_e32 v135, v13, v135
	v_mul_f32_e32 v120, v16, v120
	v_mul_f32_e32 v121, v17, v121
	v_mul_f32_e32 v122, v18, v122
	v_mul_f32_e32 v123, v19, v123
	v_mul_f32_e32 v124, v20, v124
	v_mul_f32_e32 v125, v21, v125
	v_mul_f32_e32 v126, v22, v126
	v_mul_f32_e32 v127, v23, v127
	v_mul_f32_e32 v128, v24, v128
	v_mul_f32_e32 v129, v25, v129
	v_mul_f32_e32 v130, v26, v130
	v_mul_f32_e32 v131, v27, v131
	v_mul_f32_e32 v132, v28, v132
	v_mul_f32_e32 v133, v29, v133
	v_mul_f32_e32 v134, v30, v134
	v_mul_f32_e32 v135, v31, v135
	v_fma_f32 v120, v64, v120, v80
	v_fma_f32 v121, v65, v121, v81
	v_fma_f32 v122, v66, v122, v82
	v_fma_f32 v123, v67, v123, v83
	v_fma_f32 v124, v68, v124, v84
	v_fma_f32 v125, v69, v125, v85
	v_fma_f32 v126, v70, v126, v86
	v_fma_f32 v127, v71, v127, v87
	v_fma_f32 v128, v72, v128, v88
	v_fma_f32 v129, v73, v129, v89
	v_fma_f32 v130, v74, v130, v90
	v_fma_f32 v131, v75, v131, v91
	v_fma_f32 v132, v76, v132, v92
	v_fma_f32 v133, v77, v133, v93
	v_fma_f32 v134, v78, v134, v94
	v_fma_f32 v135, v79, v135, v95
	v_cvt_pk_bf16_f32 v120, v120, v121
	v_cvt_pk_bf16_f32 v121, v122, v123
	v_cvt_pk_bf16_f32 v122, v124, v125
	v_cvt_pk_bf16_f32 v123, v126, v127
	v_cvt_pk_bf16_f32 v124, v128, v129
	v_cvt_pk_bf16_f32 v125, v130, v131
	v_cvt_pk_bf16_f32 v126, v132, v133
	v_cvt_pk_bf16_f32 v127, v134, v135
	global_store_dwordx4 v0, v[120:123], s[12:13] sc0 sc1
	global_store_dwordx4 v0, v[124:127], s[12:13] offset:1024 sc0 sc1
	s_add_i32 s26, s26, s88
	s_cmpk_gt_i32 s26, 0x7fff
	s_cbranch_scc1 .Lp6_done
	s_branch .Lp6_e0
